# attention row-max exchange via v_permlane32_swap (no LDS drain); LayerNorm wave sums via DPP + permlane16/32 swaps instead of 6 serial ds_bpermute
# speedup vs baseline: 1.1350x; 1.0035x over previous
.Lattn_join:
	v_mov_b32_e32 v41, v40
	v_mov_b32_e32 v172, v40
	s_nop 1
	v_permlane32_swap_b32 v41, v172
	s_nop 1
	v_max_f32_e32 v51, v41, v172
	v_cmp_neq_f32_e32 vcc, v51, v117
	s_cbranch_vccz .LBB0_381
	v_sub_f32_e32 v40, v117, v51
	v_exp_f32_e32 v40, v40
	s_nop 0
	v_pk_mul_f32 v[30:31], v[30:31], v[40:41] op_sel_hi:[1,0]
	v_pk_mul_f32 v[28:29], v[28:29], v[40:41] op_sel_hi:[1,0]
	v_pk_mul_f32 v[26:27], v[26:27], v[40:41] op_sel_hi:[1,0]
	v_pk_mul_f32 v[24:25], v[24:25], v[40:41] op_sel_hi:[1,0]
	v_pk_mul_f32 v[22:23], v[22:23], v[40:41] op_sel_hi:[1,0]
	v_pk_mul_f32 v[20:21], v[20:21], v[40:41] op_sel_hi:[1,0]
	v_pk_mul_f32 v[18:19], v[18:19], v[40:41] op_sel_hi:[1,0]
	v_pk_mul_f32 v[16:17], v[16:17], v[40:41] op_sel_hi:[1,0]
	v_pk_mul_f32 v[14:15], v[14:15], v[40:41] op_sel_hi:[1,0]
	v_pk_mul_f32 v[12:13], v[12:13], v[40:41] op_sel_hi:[1,0]
	v_pk_mul_f32 v[10:11], v[10:11], v[40:41] op_sel_hi:[1,0]
	v_pk_mul_f32 v[8:9], v[8:9], v[40:41] op_sel_hi:[1,0]
	v_pk_mul_f32 v[6:7], v[6:7], v[40:41] op_sel_hi:[1,0]
	v_pk_mul_f32 v[4:5], v[4:5], v[40:41] op_sel_hi:[1,0]
	v_pk_mul_f32 v[2:3], v[2:3], v[40:41] op_sel_hi:[1,0]
	v_pk_mul_f32 v[0:1], v[0:1], v[40:41] op_sel_hi:[1,0]
	v_mul_f32_e32 v99, v99, v40

.Lscr_loop:
	s_nop 1
	v_fma_f32 v31, -v131, v175, v31
	v_fma_f32 v207, v131, v174, v207
	v_fmac_f32_e32 v31, v252, v174
	v_fmac_f32_e32 v207, v252, v175
	v_cvt_pk_bf16_f32 v98, v31, v207
	ds_write_b32 v240, v98 offset:16624
	v_fma_f32 v30, -v131, v207, v30
	v_fma_f32 v206, v131, v31, v206
	v_fmac_f32_e32 v30, v252, v31
	v_fmac_f32_e32 v206, v252, v207
	v_cvt_pk_bf16_f32 v99, v30, v206
	ds_write_b32 v240, v99 offset:16352
	v_fma_f32 v29, -v131, v206, v29
	v_fma_f32 v205, v131, v30, v205
	v_fmac_f32_e32 v29, v252, v30
	v_fmac_f32_e32 v205, v252, v206
	v_cvt_pk_bf16_f32 v98, v29, v205
	ds_write_b32 v240, v98 offset:16080
	v_fma_f32 v28, -v131, v205, v28
	v_fma_f32 v204, v131, v29, v204
	v_fmac_f32_e32 v28, v252, v29
	v_fmac_f32_e32 v204, v252, v205
	v_cvt_pk_bf16_f32 v99, v28, v204
	ds_write_b32 v240, v99 offset:15808
	s_cmp_eq_u32 s76, 0
	s_cbranch_scc1 .Lscr_noy
	v_add_f32_e32 v242, v142, v158
	v_add_f32_e32 v243, v143, v159
	v_add_f32_e32 v60, v144, v160
	v_add_f32_e32 v61, v145, v161
	v_add_f32_e32 v116, v146, v162
	v_add_f32_e32 v117, v147, v163
	v_add_f32_e32 v100, v148, v164
	v_add_f32_e32 v128, v149, v165
	v_cvt_pk_bf16_f32 v242, v242, v243
	v_cvt_pk_bf16_f32 v243, v60, v61
	v_cvt_pk_bf16_f32 v60, v116, v117
	v_cvt_pk_bf16_f32 v61, v100, v128
	global_store_dwordx2 v[246:247], v[242:243], off
	global_store_dwordx2 v[246:247], v[60:61], off offset:16
	v_lshl_add_u64 v[246:247], v[246:247], 0, s[48:49]
.Lscr_noy:
	v_fma_f32 v15, -v131, v204, v15
	v_fma_f32 v47, v131, v28, v47
	v_fmac_f32_e32 v15, v252, v28
	v_fmac_f32_e32 v47, v252, v204
	v_cvt_pk_bf16_f32 v98, v15, v47
	ds_write_b32 v240, v98 offset:15536
	v_fma_f32 v14, -v131, v47, v14
	v_fma_f32 v46, v131, v15, v46
	v_fmac_f32_e32 v14, v252, v15
	v_fmac_f32_e32 v46, v252, v47
	v_cvt_pk_bf16_f32 v99, v14, v46
	ds_write_b32 v240, v99 offset:15264
	v_fma_f32 v13, -v131, v46, v13
	v_fma_f32 v45, v131, v14, v45
	v_fmac_f32_e32 v13, v252, v14
	v_fmac_f32_e32 v45, v252, v46
	v_cvt_pk_bf16_f32 v98, v13, v45
	ds_write_b32 v240, v98 offset:14992
	v_fma_f32 v12, -v131, v45, v12
	v_fma_f32 v44, v131, v13, v44
	v_fmac_f32_e32 v12, v252, v13
	v_fmac_f32_e32 v44, v252, v45
	v_cvt_pk_bf16_f32 v99, v12, v44
	ds_write_b32 v240, v99 offset:14720
	v_fma_f32 v27, -v131, v44, v27
	v_fma_f32 v203, v131, v12, v203
	v_fmac_f32_e32 v27, v252, v12
	v_fmac_f32_e32 v203, v252, v44
	v_cvt_pk_bf16_f32 v98, v27, v203
	ds_write_b32 v240, v98 offset:14448
	v_fma_f32 v26, -v131, v203, v26
	v_fma_f32 v202, v131, v27, v202
	v_fmac_f32_e32 v26, v252, v27
	v_fmac_f32_e32 v202, v252, v203
	v_cvt_pk_bf16_f32 v99, v26, v202
	ds_write_b32 v240, v99 offset:14176
	v_fma_f32 v25, -v131, v202, v25
	v_fma_f32 v201, v131, v26, v201
	v_fmac_f32_e32 v25, v252, v26
	v_fmac_f32_e32 v201, v252, v202
	v_cvt_pk_bf16_f32 v98, v25, v201
	ds_write_b32 v240, v98 offset:13904
	v_fma_f32 v24, -v131, v201, v24
	v_fma_f32 v200, v131, v25, v200
	v_fmac_f32_e32 v24, v252, v25
	v_fmac_f32_e32 v200, v252, v201
	v_cvt_pk_bf16_f32 v99, v24, v200
	ds_write_b32 v240, v99 offset:13632
	v_fma_f32 v11, -v131, v200, v11
	v_fma_f32 v43, v131, v24, v43
	v_fmac_f32_e32 v11, v252, v24
	v_fmac_f32_e32 v43, v252, v200
	v_cvt_pk_bf16_f32 v98, v11, v43
	ds_write_b32 v240, v98 offset:13360
	v_fma_f32 v10, -v131, v43, v10
	v_fma_f32 v42, v131, v11, v42
	v_fmac_f32_e32 v10, v252, v11
	v_fmac_f32_e32 v42, v252, v43
	v_cvt_pk_bf16_f32 v99, v10, v42
	ds_write_b32 v240, v99 offset:13088
	v_fma_f32 v9, -v131, v42, v9
	v_fma_f32 v41, v131, v10, v41
	v_fmac_f32_e32 v9, v252, v10
	v_fmac_f32_e32 v41, v252, v42
	v_cvt_pk_bf16_f32 v98, v9, v41
	ds_write_b32 v240, v98 offset:12816
	v_fma_f32 v8, -v131, v41, v8
	v_fma_f32 v40, v131, v9, v40
	v_fmac_f32_e32 v8, v252, v9
	v_fmac_f32_e32 v40, v252, v41
	v_cvt_pk_bf16_f32 v99, v8, v40
	ds_write_b32 v240, v99 offset:12544
	v_fma_f32 v23, -v131, v40, v23
	v_fma_f32 v199, v131, v8, v199
	v_fmac_f32_e32 v23, v252, v8
	v_fmac_f32_e32 v199, v252, v40
	v_cvt_pk_bf16_f32 v98, v23, v199
	ds_write_b32 v240, v98 offset:12272
	v_fma_f32 v22, -v131, v199, v22
	v_fma_f32 v198, v131, v23, v198
	v_fmac_f32_e32 v22, v252, v23
	v_fmac_f32_e32 v198, v252, v199
	v_cvt_pk_bf16_f32 v99, v22, v198
	ds_write_b32 v240, v99 offset:12000
	v_fma_f32 v21, -v131, v198, v21
	v_fma_f32 v197, v131, v22, v197
	v_fmac_f32_e32 v21, v252, v22
	v_fmac_f32_e32 v197, v252, v198
	v_cvt_pk_bf16_f32 v98, v21, v197
	ds_write_b32 v240, v98 offset:11728
	v_fma_f32 v20, -v131, v197, v20
	v_fma_f32 v196, v131, v21, v196
	v_fmac_f32_e32 v20, v252, v21
	v_fmac_f32_e32 v196, v252, v197
	v_cvt_pk_bf16_f32 v99, v20, v196
	ds_write_b32 v240, v99 offset:11456
	v_fma_f32 v7, -v131, v196, v7
	v_fma_f32 v39, v131, v20, v39
	v_fmac_f32_e32 v7, v252, v20
	v_fmac_f32_e32 v39, v252, v196
	v_cvt_pk_bf16_f32 v98, v7, v39
	ds_write_b32 v240, v98 offset:11184
	v_fma_f32 v6, -v131, v39, v6
	v_fma_f32 v38, v131, v7, v38
	v_fmac_f32_e32 v6, v252, v7
	v_fmac_f32_e32 v38, v252, v39
	v_cvt_pk_bf16_f32 v99, v6, v38
	ds_write_b32 v240, v99 offset:10912
	v_fma_f32 v5, -v131, v38, v5
	v_fma_f32 v37, v131, v6, v37
	v_fmac_f32_e32 v5, v252, v6
	v_fmac_f32_e32 v37, v252, v38
	v_cvt_pk_bf16_f32 v98, v5, v37
	ds_write_b32 v240, v98 offset:10640
	v_fma_f32 v4, -v131, v37, v4
	v_fma_f32 v36, v131, v5, v36
	v_fmac_f32_e32 v4, v252, v5
	v_fmac_f32_e32 v36, v252, v37
	v_cvt_pk_bf16_f32 v99, v4, v36
	ds_write_b32 v240, v99 offset:10368
	v_fma_f32 v19, -v131, v36, v19
	v_fma_f32 v195, v131, v4, v195
	v_fmac_f32_e32 v19, v252, v4
	v_fmac_f32_e32 v195, v252, v36
	v_cvt_pk_bf16_f32 v98, v19, v195
	ds_write_b32 v240, v98 offset:10096
	v_fma_f32 v18, -v131, v195, v18
	v_fma_f32 v194, v131, v19, v194
	v_fmac_f32_e32 v18, v252, v19
	v_fmac_f32_e32 v194, v252, v195
	v_cvt_pk_bf16_f32 v99, v18, v194
	ds_write_b32 v240, v99 offset:9824
	v_fma_f32 v17, -v131, v194, v17
	v_fma_f32 v193, v131, v18, v193
	v_fmac_f32_e32 v17, v252, v18
	v_fmac_f32_e32 v193, v252, v194
	v_cvt_pk_bf16_f32 v98, v17, v193
	ds_write_b32 v240, v98 offset:9552
	v_fma_f32 v16, -v131, v193, v16
	v_fma_f32 v192, v131, v17, v192
	v_fmac_f32_e32 v16, v252, v17
	v_fmac_f32_e32 v192, v252, v193
	v_cvt_pk_bf16_f32 v99, v16, v192
	ds_write_b32 v240, v99 offset:9280
	v_fma_f32 v3, -v131, v192, v3
	v_fma_f32 v35, v131, v16, v35
	v_fmac_f32_e32 v3, v252, v16
	v_fmac_f32_e32 v35, v252, v192
	v_cvt_pk_bf16_f32 v98, v3, v35
	ds_write_b32 v240, v98 offset:9008
	v_fma_f32 v2, -v131, v35, v2
	v_fma_f32 v34, v131, v3, v34
	v_fmac_f32_e32 v2, v252, v3
	v_fmac_f32_e32 v34, v252, v35
	v_cvt_pk_bf16_f32 v99, v2, v34
	ds_write_b32 v240, v99 offset:8736
	v_fma_f32 v1, -v131, v34, v1
	v_fma_f32 v33, v131, v2, v33
	v_fmac_f32_e32 v1, v252, v2
	v_fmac_f32_e32 v33, v252, v34
	v_cvt_pk_bf16_f32 v98, v1, v33
	ds_write_b32 v240, v98 offset:8464
	v_fma_f32 v174, -v131, v33, v0
	v_fma_f32 v175, v131, v1, v32
	v_fmac_f32_e32 v174, v252, v1
	v_fmac_f32_e32 v175, v252, v33
	v_cvt_pk_bf16_f32 v99, v174, v175
	ds_write_b32 v240, v99 offset:8192
	s_waitcnt vmcnt(2)
	v_mov_b64_e32 v[48:49], v[52:53]
	v_mov_b64_e32 v[50:51], v[54:55]
	s_cmp_lt_u32 s77, s39
	s_cselect_b32 s46, s48, 0
	s_cselect_b32 s47, s49, 0
	s_add_i32 s77, s77, 1
	v_lshl_add_u64 v[244:245], v[244:245], 0, s[46:47]
	global_load_dwordx4 v[52:55], v[244:245], off
	v_mfma_f32_32x32x16_bf16 v[0:15], v[48:51], v[110:113], 0
	v_mfma_f32_32x32x16_bf16 v[16:31], v[48:51], v[102:105], 0
	v_mfma_f32_32x32x16_bf16 v[32:47], v[48:51], v[106:109], 0
	v_mfma_f32_32x32x16_bf16 v[192:207], v[48:51], v[94:97], 0
	ds_read_b128 v[208:211], v241 offset:8192
	ds_read_b128 v[212:215], v241 offset:8224
	ds_read_b128 v[216:219], v241 offset:8256
	ds_read_b128 v[220:223], v241 offset:8288
	ds_read_b128 v[224:227], v241 offset:8320
	ds_read_b128 v[228:231], v241 offset:8352
	ds_read_b128 v[232:235], v241 offset:8384
	ds_read_b128 v[236:239], v241 offset:8416
	s_waitcnt lgkmcnt(7)
	v_mfma_f32_32x32x16_bf16 v[142:157], v[90:93], v[208:211], 0
	v_permlane32_swap_b32 v0, v16
	v_permlane32_swap_b32 v1, v17
	v_permlane32_swap_b32 v2, v18
	v_permlane32_swap_b32 v3, v19
	s_waitcnt lgkmcnt(6)
	v_mfma_f32_32x32x16_bf16 v[158:173], v[86:89], v[212:215], 0
	v_permlane32_swap_b32 v4, v20
	v_permlane32_swap_b32 v5, v21
	v_permlane32_swap_b32 v6, v22
	v_permlane32_swap_b32 v7, v23
	s_waitcnt lgkmcnt(5)
	v_mfma_f32_32x32x16_bf16 v[142:157], v[82:85], v[216:219], v[142:157]
	v_permlane32_swap_b32 v8, v24
	v_permlane32_swap_b32 v9, v25
	v_permlane32_swap_b32 v10, v26
	v_permlane32_swap_b32 v11, v27
	s_waitcnt lgkmcnt(4)
	v_mfma_f32_32x32x16_bf16 v[158:173], v[78:81], v[220:223], v[158:173]
	v_permlane32_swap_b32 v12, v28
	v_permlane32_swap_b32 v13, v29
	v_permlane32_swap_b32 v14, v30
	v_permlane32_swap_b32 v15, v31
	s_waitcnt lgkmcnt(3)
	v_mfma_f32_32x32x16_bf16 v[142:157], v[74:77], v[224:227], v[142:157]
	v_permlane32_swap_b32 v32, v192
	v_permlane32_swap_b32 v33, v193
	v_permlane32_swap_b32 v34, v194
	v_permlane32_swap_b32 v35, v195
	s_waitcnt lgkmcnt(2)
	v_mfma_f32_32x32x16_bf16 v[158:173], v[70:73], v[228:231], v[158:173]
	v_permlane32_swap_b32 v36, v196
	v_permlane32_swap_b32 v37, v197
	v_permlane32_swap_b32 v38, v198
	v_permlane32_swap_b32 v39, v199
	s_waitcnt lgkmcnt(1)
	v_mfma_f32_32x32x16_bf16 v[142:157], v[66:69], v[232:235], v[142:157]
	v_permlane32_swap_b32 v40, v200
	v_permlane32_swap_b32 v41, v201
	v_permlane32_swap_b32 v42, v202
	v_permlane32_swap_b32 v43, v203
	s_waitcnt lgkmcnt(0)
	v_mfma_f32_32x32x16_bf16 v[158:173], v[62:65], v[236:239], v[158:173]
	v_permlane32_swap_b32 v44, v204
	v_permlane32_swap_b32 v45, v205
	v_permlane32_swap_b32 v46, v206
	v_permlane32_swap_b32 v47, v207
	s_add_i32 s76, s76, 1
	s_cmp_lt_u32 s76, s39
	s_cbranch_scc1 .Lscr_loop
	s_nop 15
	v_add_f32_e32 v242, v142, v158
	v_add_f32_e32 v243, v143, v159
	v_add_f32_e32 v60, v144, v160
	v_add_f32_e32 v61, v145, v161
	v_add_f32_e32 v116, v146, v162
	v_add_f32_e32 v117, v147, v163
	v_add_f32_e32 v100, v148, v164
	v_add_f32_e32 v128, v149, v165
	v_cvt_pk_bf16_f32 v242, v242, v243
	v_cvt_pk_bf16_f32 v243, v60, v61
	v_cvt_pk_bf16_f32 v60, v116, v117
	v_cvt_pk_bf16_f32 v61, v100, v128
	global_store_dwordx2 v[246:247], v[242:243], off
	global_store_dwordx2 v[246:247], v[60:61], off offset:16
	v_lshl_add_u64 v[246:247], v[246:247], 0, s[48:49]
	v_mov_b32_e32 v114, v174
	v_mov_b32_e32 v115, v175
	s_branch .LBB0_629

.Lscf_loop:
	s_nop 1
	v_fma_f32 v0, -v131, v175, v0
	v_fma_f32 v32, v131, v174, v32
	v_fmac_f32_e32 v0, v252, v174
	v_fmac_f32_e32 v32, v252, v175
	v_cvt_pk_bf16_f32 v98, v0, v32
	ds_write_b32 v240, v98 offset:8192
	v_fma_f32 v1, -v131, v32, v1
	v_fma_f32 v33, v131, v0, v33
	v_fmac_f32_e32 v1, v252, v0
	v_fmac_f32_e32 v33, v252, v32
	v_cvt_pk_bf16_f32 v99, v1, v33
	ds_write_b32 v240, v99 offset:8464
	v_fma_f32 v2, -v131, v33, v2
	v_fma_f32 v34, v131, v1, v34
	v_fmac_f32_e32 v2, v252, v1
	v_fmac_f32_e32 v34, v252, v33
	v_cvt_pk_bf16_f32 v98, v2, v34
	ds_write_b32 v240, v98 offset:8736
	v_fma_f32 v3, -v131, v34, v3
	v_fma_f32 v35, v131, v2, v35
	v_fmac_f32_e32 v3, v252, v2
	v_fmac_f32_e32 v35, v252, v34
	v_cvt_pk_bf16_f32 v99, v3, v35
	ds_write_b32 v240, v99 offset:9008
	s_cmp_eq_u32 s76, 0
	s_cbranch_scc1 .Lscf_noy
	v_add_f32_e32 v242, v142, v158
	v_add_f32_e32 v243, v143, v159
	v_add_f32_e32 v60, v144, v160
	v_add_f32_e32 v61, v145, v161
	v_add_f32_e32 v116, v146, v162
	v_add_f32_e32 v117, v147, v163
	v_add_f32_e32 v100, v148, v164
	v_add_f32_e32 v128, v149, v165
	v_cvt_pk_bf16_f32 v242, v242, v243
	v_cvt_pk_bf16_f32 v243, v60, v61
	v_cvt_pk_bf16_f32 v60, v116, v117
	v_cvt_pk_bf16_f32 v61, v100, v128
	global_store_dwordx2 v[246:247], v[242:243], off
	global_store_dwordx2 v[246:247], v[60:61], off offset:16
	v_lshl_add_u64 v[246:247], v[246:247], 0, s[48:49]
.Lscf_noy:
	v_fma_f32 v16, -v131, v35, v16
	v_fma_f32 v192, v131, v3, v192
	v_fmac_f32_e32 v16, v252, v3
	v_fmac_f32_e32 v192, v252, v35
	v_cvt_pk_bf16_f32 v98, v16, v192
	ds_write_b32 v240, v98 offset:9280
	v_fma_f32 v17, -v131, v192, v17
	v_fma_f32 v193, v131, v16, v193
	v_fmac_f32_e32 v17, v252, v16
	v_fmac_f32_e32 v193, v252, v192
	v_cvt_pk_bf16_f32 v99, v17, v193
	ds_write_b32 v240, v99 offset:9552
	v_fma_f32 v18, -v131, v193, v18
	v_fma_f32 v194, v131, v17, v194
	v_fmac_f32_e32 v18, v252, v17
	v_fmac_f32_e32 v194, v252, v193
	v_cvt_pk_bf16_f32 v98, v18, v194
	ds_write_b32 v240, v98 offset:9824
	v_fma_f32 v19, -v131, v194, v19
	v_fma_f32 v195, v131, v18, v195
	v_fmac_f32_e32 v19, v252, v18
	v_fmac_f32_e32 v195, v252, v194
	v_cvt_pk_bf16_f32 v99, v19, v195
	ds_write_b32 v240, v99 offset:10096
	v_fma_f32 v4, -v131, v195, v4
	v_fma_f32 v36, v131, v19, v36
	v_fmac_f32_e32 v4, v252, v19
	v_fmac_f32_e32 v36, v252, v195
	v_cvt_pk_bf16_f32 v98, v4, v36
	ds_write_b32 v240, v98 offset:10368
	v_fma_f32 v5, -v131, v36, v5
	v_fma_f32 v37, v131, v4, v37
	v_fmac_f32_e32 v5, v252, v4
	v_fmac_f32_e32 v37, v252, v36
	v_cvt_pk_bf16_f32 v99, v5, v37
	ds_write_b32 v240, v99 offset:10640
	v_fma_f32 v6, -v131, v37, v6
	v_fma_f32 v38, v131, v5, v38
	v_fmac_f32_e32 v6, v252, v5
	v_fmac_f32_e32 v38, v252, v37
	v_cvt_pk_bf16_f32 v98, v6, v38
	ds_write_b32 v240, v98 offset:10912
	v_fma_f32 v7, -v131, v38, v7
	v_fma_f32 v39, v131, v6, v39
	v_fmac_f32_e32 v7, v252, v6
	v_fmac_f32_e32 v39, v252, v38
	v_cvt_pk_bf16_f32 v99, v7, v39
	ds_write_b32 v240, v99 offset:11184
	v_fma_f32 v20, -v131, v39, v20
	v_fma_f32 v196, v131, v7, v196
	v_fmac_f32_e32 v20, v252, v7
	v_fmac_f32_e32 v196, v252, v39
	v_cvt_pk_bf16_f32 v98, v20, v196
	ds_write_b32 v240, v98 offset:11456
	v_fma_f32 v21, -v131, v196, v21
	v_fma_f32 v197, v131, v20, v197
	v_fmac_f32_e32 v21, v252, v20
	v_fmac_f32_e32 v197, v252, v196
	v_cvt_pk_bf16_f32 v99, v21, v197
	ds_write_b32 v240, v99 offset:11728
	v_fma_f32 v22, -v131, v197, v22
	v_fma_f32 v198, v131, v21, v198
	v_fmac_f32_e32 v22, v252, v21
	v_fmac_f32_e32 v198, v252, v197
	v_cvt_pk_bf16_f32 v98, v22, v198
	ds_write_b32 v240, v98 offset:12000
	v_fma_f32 v23, -v131, v198, v23
	v_fma_f32 v199, v131, v22, v199
	v_fmac_f32_e32 v23, v252, v22
	v_fmac_f32_e32 v199, v252, v198
	v_cvt_pk_bf16_f32 v99, v23, v199
	ds_write_b32 v240, v99 offset:12272
	v_fma_f32 v8, -v131, v199, v8
	v_fma_f32 v40, v131, v23, v40
	v_fmac_f32_e32 v8, v252, v23
	v_fmac_f32_e32 v40, v252, v199
	v_cvt_pk_bf16_f32 v98, v8, v40
	ds_write_b32 v240, v98 offset:12544
	v_fma_f32 v9, -v131, v40, v9
	v_fma_f32 v41, v131, v8, v41
	v_fmac_f32_e32 v9, v252, v8
	v_fmac_f32_e32 v41, v252, v40
	v_cvt_pk_bf16_f32 v99, v9, v41
	ds_write_b32 v240, v99 offset:12816
	v_fma_f32 v10, -v131, v41, v10
	v_fma_f32 v42, v131, v9, v42
	v_fmac_f32_e32 v10, v252, v9
	v_fmac_f32_e32 v42, v252, v41
	v_cvt_pk_bf16_f32 v98, v10, v42
	ds_write_b32 v240, v98 offset:13088
	v_fma_f32 v11, -v131, v42, v11
	v_fma_f32 v43, v131, v10, v43
	v_fmac_f32_e32 v11, v252, v10
	v_fmac_f32_e32 v43, v252, v42
	v_cvt_pk_bf16_f32 v99, v11, v43
	ds_write_b32 v240, v99 offset:13360
	v_fma_f32 v24, -v131, v43, v24
	v_fma_f32 v200, v131, v11, v200
	v_fmac_f32_e32 v24, v252, v11
	v_fmac_f32_e32 v200, v252, v43
	v_cvt_pk_bf16_f32 v98, v24, v200
	ds_write_b32 v240, v98 offset:13632
	v_fma_f32 v25, -v131, v200, v25
	v_fma_f32 v201, v131, v24, v201
	v_fmac_f32_e32 v25, v252, v24
	v_fmac_f32_e32 v201, v252, v200
	v_cvt_pk_bf16_f32 v99, v25, v201
	ds_write_b32 v240, v99 offset:13904
	v_fma_f32 v26, -v131, v201, v26
	v_fma_f32 v202, v131, v25, v202
	v_fmac_f32_e32 v26, v252, v25
	v_fmac_f32_e32 v202, v252, v201
	v_cvt_pk_bf16_f32 v98, v26, v202
	ds_write_b32 v240, v98 offset:14176
	v_fma_f32 v27, -v131, v202, v27
	v_fma_f32 v203, v131, v26, v203
	v_fmac_f32_e32 v27, v252, v26
	v_fmac_f32_e32 v203, v252, v202
	v_cvt_pk_bf16_f32 v99, v27, v203
	ds_write_b32 v240, v99 offset:14448
	v_fma_f32 v12, -v131, v203, v12
	v_fma_f32 v44, v131, v27, v44
	v_fmac_f32_e32 v12, v252, v27
	v_fmac_f32_e32 v44, v252, v203
	v_cvt_pk_bf16_f32 v98, v12, v44
	ds_write_b32 v240, v98 offset:14720
	v_fma_f32 v13, -v131, v44, v13
	v_fma_f32 v45, v131, v12, v45
	v_fmac_f32_e32 v13, v252, v12
	v_fmac_f32_e32 v45, v252, v44
	v_cvt_pk_bf16_f32 v99, v13, v45
	ds_write_b32 v240, v99 offset:14992
	v_fma_f32 v14, -v131, v45, v14
	v_fma_f32 v46, v131, v13, v46
	v_fmac_f32_e32 v14, v252, v13
	v_fmac_f32_e32 v46, v252, v45
	v_cvt_pk_bf16_f32 v98, v14, v46
	ds_write_b32 v240, v98 offset:15264
	v_fma_f32 v15, -v131, v46, v15
	v_fma_f32 v47, v131, v14, v47
	v_fmac_f32_e32 v15, v252, v14
	v_fmac_f32_e32 v47, v252, v46
	v_cvt_pk_bf16_f32 v99, v15, v47
	ds_write_b32 v240, v99 offset:15536
	v_fma_f32 v28, -v131, v47, v28
	v_fma_f32 v204, v131, v15, v204
	v_fmac_f32_e32 v28, v252, v15
	v_fmac_f32_e32 v204, v252, v47
	v_cvt_pk_bf16_f32 v98, v28, v204
	ds_write_b32 v240, v98 offset:15808
	v_fma_f32 v29, -v131, v204, v29
	v_fma_f32 v205, v131, v28, v205
	v_fmac_f32_e32 v29, v252, v28
	v_fmac_f32_e32 v205, v252, v204
	v_cvt_pk_bf16_f32 v99, v29, v205
	ds_write_b32 v240, v99 offset:16080
	v_fma_f32 v30, -v131, v205, v30
	v_fma_f32 v206, v131, v29, v206
	v_fmac_f32_e32 v30, v252, v29
	v_fmac_f32_e32 v206, v252, v205
	v_cvt_pk_bf16_f32 v98, v30, v206
	ds_write_b32 v240, v98 offset:16352
	v_fma_f32 v174, -v131, v206, v31
	v_fma_f32 v175, v131, v30, v207
	v_fmac_f32_e32 v174, v252, v30
	v_fmac_f32_e32 v175, v252, v206
	v_cvt_pk_bf16_f32 v99, v174, v175
	ds_write_b32 v240, v99 offset:16624
	s_waitcnt vmcnt(2)
	v_mov_b64_e32 v[48:49], v[52:53]
	v_mov_b64_e32 v[50:51], v[54:55]
	s_cmp_lt_u32 s77, s39
	s_cselect_b32 s46, s48, 0
	s_cselect_b32 s47, s49, 0
	s_add_i32 s77, s77, 1
	v_lshl_add_u64 v[244:245], v[244:245], 0, s[46:47]
	global_load_dwordx4 v[52:55], v[244:245], off
	v_mfma_f32_32x32x16_bf16 v[0:15], v[48:51], v[110:113], 0
	v_mfma_f32_32x32x16_bf16 v[16:31], v[48:51], v[102:105], 0
	v_mfma_f32_32x32x16_bf16 v[32:47], v[48:51], v[106:109], 0
	v_mfma_f32_32x32x16_bf16 v[192:207], v[48:51], v[94:97], 0
	ds_read_b128 v[208:211], v241 offset:8192
	ds_read_b128 v[212:215], v241 offset:8224
	ds_read_b128 v[216:219], v241 offset:8256
	ds_read_b128 v[220:223], v241 offset:8288
	ds_read_b128 v[224:227], v241 offset:8320
	ds_read_b128 v[228:231], v241 offset:8352
	ds_read_b128 v[232:235], v241 offset:8384
	ds_read_b128 v[236:239], v241 offset:8416
	s_waitcnt lgkmcnt(7)
	v_mfma_f32_32x32x16_bf16 v[142:157], v[90:93], v[208:211], 0
	v_permlane32_swap_b32 v0, v16
	v_permlane32_swap_b32 v1, v17
	v_permlane32_swap_b32 v2, v18
	v_permlane32_swap_b32 v3, v19
	s_waitcnt lgkmcnt(6)
	v_mfma_f32_32x32x16_bf16 v[158:173], v[86:89], v[212:215], 0
	v_permlane32_swap_b32 v4, v20
	v_permlane32_swap_b32 v5, v21
	v_permlane32_swap_b32 v6, v22
	v_permlane32_swap_b32 v7, v23
	s_waitcnt lgkmcnt(5)
	v_mfma_f32_32x32x16_bf16 v[142:157], v[82:85], v[216:219], v[142:157]
	v_permlane32_swap_b32 v8, v24
	v_permlane32_swap_b32 v9, v25
	v_permlane32_swap_b32 v10, v26
	v_permlane32_swap_b32 v11, v27
	s_waitcnt lgkmcnt(4)
	v_mfma_f32_32x32x16_bf16 v[158:173], v[78:81], v[220:223], v[158:173]
	v_permlane32_swap_b32 v12, v28
	v_permlane32_swap_b32 v13, v29
	v_permlane32_swap_b32 v14, v30
	v_permlane32_swap_b32 v15, v31
	s_waitcnt lgkmcnt(3)
	v_mfma_f32_32x32x16_bf16 v[142:157], v[74:77], v[224:227], v[142:157]
	v_permlane32_swap_b32 v32, v192
	v_permlane32_swap_b32 v33, v193
	v_permlane32_swap_b32 v34, v194
	v_permlane32_swap_b32 v35, v195
	s_waitcnt lgkmcnt(2)
	v_mfma_f32_32x32x16_bf16 v[158:173], v[70:73], v[228:231], v[158:173]
	v_permlane32_swap_b32 v36, v196
	v_permlane32_swap_b32 v37, v197
	v_permlane32_swap_b32 v38, v198
	v_permlane32_swap_b32 v39, v199
	s_waitcnt lgkmcnt(1)
	v_mfma_f32_32x32x16_bf16 v[142:157], v[66:69], v[232:235], v[142:157]
	v_permlane32_swap_b32 v40, v200
	v_permlane32_swap_b32 v41, v201
	v_permlane32_swap_b32 v42, v202
	v_permlane32_swap_b32 v43, v203
	s_waitcnt lgkmcnt(0)
	v_mfma_f32_32x32x16_bf16 v[158:173], v[62:65], v[236:239], v[158:173]
	v_permlane32_swap_b32 v44, v204
	v_permlane32_swap_b32 v45, v205
	v_permlane32_swap_b32 v46, v206
	v_permlane32_swap_b32 v47, v207
	s_add_i32 s76, s76, 1
	s_cmp_lt_u32 s76, s39
	s_cbranch_scc1 .Lscf_loop
	s_nop 15
	v_add_f32_e32 v242, v142, v158
	v_add_f32_e32 v243, v143, v159
	v_add_f32_e32 v60, v144, v160
	v_add_f32_e32 v61, v145, v161
	v_add_f32_e32 v116, v146, v162
	v_add_f32_e32 v117, v147, v163
	v_add_f32_e32 v100, v148, v164
	v_add_f32_e32 v128, v149, v165
	v_cvt_pk_bf16_f32 v242, v242, v243
	v_cvt_pk_bf16_f32 v243, v60, v61
	v_cvt_pk_bf16_f32 v60, v116, v117
	v_cvt_pk_bf16_f32 v61, v100, v128
	global_store_dwordx2 v[246:247], v[242:243], off
	global_store_dwordx2 v[246:247], v[60:61], off offset:16
	v_lshl_add_u64 v[246:247], v[246:247], 0, s[48:49]
	v_mov_b32_e32 v135, v174
	v_mov_b32_e32 v101, v175
	s_branch .LBB0_631

.LBB0_930:
	s_or_b64 exec, exec, s[52:53]
	v_lshlrev_b32_e32 v54, 16, v32
	v_and_b32_e32 v55, 0xffff0000, v32
	v_add_f32_e32 v11, 0, v54
	v_lshlrev_b32_e32 v32, 16, v33
	v_add_f32_e32 v11, v11, v55
	v_and_b32_e32 v33, 0xffff0000, v33
	v_add_f32_e32 v11, v11, v32
	v_lshlrev_b32_e32 v56, 16, v30
	v_add_f32_e32 v11, v11, v33
	v_and_b32_e32 v57, 0xffff0000, v30
	v_add_f32_e32 v11, v11, v56
	v_lshlrev_b32_e32 v30, 16, v31
	v_add_f32_e32 v11, v11, v57
	v_and_b32_e32 v31, 0xffff0000, v31
	v_add_f32_e32 v11, v11, v30
	v_lshlrev_b32_e32 v58, 16, v28
	v_add_f32_e32 v11, v11, v31
	v_and_b32_e32 v59, 0xffff0000, v28
	v_add_f32_e32 v11, v11, v58
	v_lshlrev_b32_e32 v60, 16, v29
	v_add_f32_e32 v11, v11, v59
	v_and_b32_e32 v61, 0xffff0000, v29
	v_add_f32_e32 v11, v11, v60
	v_lshlrev_b32_e32 v62, 16, v26
	v_add_f32_e32 v11, v11, v61
	v_and_b32_e32 v63, 0xffff0000, v26
	v_add_f32_e32 v11, v11, v62
	v_lshlrev_b32_e32 v64, 16, v27
	v_add_f32_e32 v11, v11, v63
	v_and_b32_e32 v65, 0xffff0000, v27
	v_add_f32_e32 v11, v11, v64
	v_add_f32_e32 v11, v11, v65
	v_cmp_lt_i32_e32 vcc, s22, v24
	s_and_b64 s[38:39], exec, s[44:45]
	s_or_b64 s[50:51], s[38:39], s[50:51]
	s_waitcnt lgkmcnt(0)
	v_lshl_add_u64 v[78:79], v[0:1], 0, v[6:7]
	s_mov_b32 s3, 0x1d600000
	v_mov_b32_e32 v15, v129
	v_lshl_add_u64 v[8:9], v[8:9], 0, s[4:5]
	v_lshl_add_u64 v[0:1], v[0:1], 0, s[4:5]
	s_nop 1
	v_add_f32_dpp v11, v11, v11 quad_perm:[1,0,3,2] row_mask:0xf bank_mask:0xf
	s_nop 1
	v_add_f32_dpp v11, v11, v11 quad_perm:[2,3,0,1] row_mask:0xf bank_mask:0xf
	s_nop 1
	v_add_f32_dpp v11, v11, v11 row_half_mirror row_mask:0xf bank_mask:0xf
	s_nop 1
	v_add_f32_dpp v11, v11, v11 row_mirror row_mask:0xf bank_mask:0xf
	s_nop 1
	v_mov_b32_e32 v13, v11
	v_mov_b32_e32 v250, v11
	s_nop 1
	v_permlane16_swap_b32 v13, v250
	s_nop 1
	v_add_f32_e32 v11, v13, v250
	v_mov_b32_e32 v13, v11
	v_mov_b32_e32 v250, v11
	s_nop 1
	v_permlane32_swap_b32 v13, v250
	s_nop 1
	v_add_f32_e32 v11, v13, v250
	v_mul_f32_e32 v66, 0x3a800000, v11
	v_add_u32_e32 v11, 0xffffe000, v24
	v_lshrrev_b32_e32 v11, 12, v11
	v_add_u32_e32 v11, 1, v11
	v_cndmask_b32_e32 v11, 0, v11, vcc
	v_mov_b64_e32 v[24:25], s[48:49]
	v_mad_u64_u32 v[24:25], s[38:39], v11, s23, v[24:25]
	s_mov_b64 s[38:39], 0x1000
	s_nop 0
	v_lshl_add_u64 v[68:69], v[24:25], 0, s[38:39]
	v_lshl_add_u64 v[24:25], v[24:25], 0, v[128:129]
	v_lshl_add_u64 v[26:27], v[68:69], 0, v[128:129]
	v_pk_add_f32 v[54:55], v[54:55], v[66:67] op_sel_hi:[1,0] neg_lo:[0,1] neg_hi:[0,1]
	v_pk_add_f32 v[32:33], v[32:33], v[66:67] op_sel_hi:[1,0] neg_lo:[0,1] neg_hi:[0,1]
	v_pk_mul_f32 v[72:73], v[54:55], v[54:55]
	v_mov_b32_e32 v11, v129
	v_pk_mul_f32 v[70:71], v[32:33], v[32:33]
	v_lshl_add_u64 v[80:81], v[68:69], 0, v[10:11]
	v_add_f32_e32 v11, v72, v73
	v_pk_add_f32 v[56:57], v[56:57], v[66:67] op_sel_hi:[1,0] neg_lo:[0,1] neg_hi:[0,1]
	v_add_f32_e32 v11, v70, v11
	v_pk_mul_f32 v[86:87], v[56:57], v[56:57]
	v_add_f32_e32 v11, v71, v11
	v_pk_add_f32 v[82:83], v[30:31], v[66:67] op_sel_hi:[1,0] neg_lo:[0,1] neg_hi:[0,1]
	v_add_f32_e32 v11, v86, v11
	v_pk_mul_f32 v[84:85], v[82:83], v[82:83]
	v_add_f32_e32 v11, v87, v11
	v_pk_add_f32 v[58:59], v[58:59], v[66:67] op_sel_hi:[1,0] neg_lo:[0,1] neg_hi:[0,1]
	v_add_f32_e32 v11, v84, v11
	v_pk_mul_f32 v[92:93], v[58:59], v[58:59]
	v_add_f32_e32 v11, v85, v11
	v_pk_add_f32 v[60:61], v[60:61], v[66:67] op_sel_hi:[1,0] neg_lo:[0,1] neg_hi:[0,1]
	v_add_f32_e32 v11, v92, v11
	v_pk_mul_f32 v[90:91], v[60:61], v[60:61]
	v_add_f32_e32 v11, v93, v11
	v_pk_add_f32 v[30:31], v[62:63], v[66:67] op_sel_hi:[1,0] neg_lo:[0,1] neg_hi:[0,1]
	v_add_f32_e32 v11, v90, v11
	v_pk_mul_f32 v[62:63], v[30:31], v[30:31]
	v_add_f32_e32 v11, v91, v11
	v_add_f32_e32 v11, v62, v11
	v_add_f32_e32 v11, v63, v11
	v_mov_b32_e32 v13, v129
	v_lshl_add_u64 v[88:89], v[68:69], 0, v[12:13]
	v_pk_add_f32 v[28:29], v[64:65], v[66:67] op_sel_hi:[1,0] neg_lo:[0,1] neg_hi:[0,1]
	v_pk_mul_f32 v[64:65], v[28:29], v[28:29]
	v_lshl_add_u64 v[26:27], v[68:69], 0, v[14:15]
	v_add_f32_e32 v11, v64, v11
	v_add_f32_e32 v11, v65, v11
	s_waitcnt lgkmcnt(0)
	s_nop 1
	v_add_f32_dpp v11, v11, v11 quad_perm:[1,0,3,2] row_mask:0xf bank_mask:0xf
	s_nop 1
	v_add_f32_dpp v11, v11, v11 quad_perm:[2,3,0,1] row_mask:0xf bank_mask:0xf
	s_nop 1
	v_add_f32_dpp v11, v11, v11 row_half_mirror row_mask:0xf bank_mask:0xf
	s_nop 1
	v_add_f32_dpp v11, v11, v11 row_mirror row_mask:0xf bank_mask:0xf
	s_nop 1
	v_mov_b32_e32 v13, v11
	v_mov_b32_e32 v250, v11
	s_nop 1
	v_permlane16_swap_b32 v13, v250
	s_nop 1
	v_add_f32_e32 v11, v13, v250
	v_mov_b32_e32 v13, v11
	v_mov_b32_e32 v250, v11
	s_nop 1
	v_permlane32_swap_b32 v13, v250
	s_nop 1
	v_add_f32_e32 v11, v13, v250
	v_fmamk_f32 v11, v11, 0x3a800000, v182
	v_cmp_gt_f32_e32 vcc, s13, v11
	v_mul_f32_e32 v13, 0x4b800000, v11
	s_nop 0
	v_cndmask_b32_e32 v11, v11, v13, vcc
	v_rsq_f32_e32 v11, v11
	s_nop 0
	v_mul_f32_e32 v13, 0x45800000, v11
	v_cndmask_b32_e32 v62, v11, v13, vcc
	s_waitcnt vmcnt(4)
	v_pk_mul_f32 v[168:169], v[54:55], v[62:63] op_sel_hi:[1,0]
	v_pk_mul_f32 v[170:171], v[32:33], v[62:63] op_sel_hi:[1,0]
	v_add_co_u32_e32 v32, vcc, s25, v78
	s_nop 1
	v_addc_co_u32_e32 v33, vcc, 0, v79, vcc
	v_add_co_u32_e32 v50, vcc, s3, v78
	s_nop 1
	v_addc_co_u32_e32 v51, vcc, 0, v79, vcc
	v_pk_add_f32 v[172:173], v[152:153], 1.0 op_sel_hi:[1,0]
	v_pk_add_f32 v[174:175], v[154:155], 1.0 op_sel_hi:[1,0]
	v_pk_fma_f32 v[168:169], v[96:97], v[168:169], v[112:113]
	v_pk_fma_f32 v[170:171], v[98:99], v[170:171], v[114:115]
	s_nop 0
	v_pk_fma_f32 v[192:193], v[172:173], v[168:169], v[136:137]
	v_pk_fma_f32 v[194:195], v[174:175], v[170:171], v[138:139]
	v_cvt_pk_bf16_f32 v196, v168, v169
	v_cvt_pk_bf16_f32 v197, v170, v171
	v_cvt_pk_bf16_f32 v198, v192, v193
	v_cvt_pk_bf16_f32 v199, v194, v195
	global_store_dwordx2 v[32:33], v[196:197], off
	global_store_dwordx2 v[50:51], v[198:199], off
	v_pk_mul_f32 v[168:169], v[56:57], v[62:63] op_sel_hi:[1,0]
	v_pk_mul_f32 v[170:171], v[82:83], v[62:63] op_sel_hi:[1,0]
	v_pk_add_f32 v[172:173], v[156:157], 1.0 op_sel_hi:[1,0]
	v_pk_add_f32 v[174:175], v[158:159], 1.0 op_sel_hi:[1,0]
	v_pk_fma_f32 v[168:169], v[100:101], v[168:169], v[116:117]
	v_pk_fma_f32 v[170:171], v[102:103], v[170:171], v[118:119]
	s_nop 0
	v_pk_fma_f32 v[192:193], v[172:173], v[168:169], v[140:141]
	v_pk_fma_f32 v[194:195], v[174:175], v[170:171], v[142:143]
	v_cvt_pk_bf16_f32 v200, v168, v169
	v_cvt_pk_bf16_f32 v201, v170, v171
	v_cvt_pk_bf16_f32 v202, v192, v193
	v_cvt_pk_bf16_f32 v203, v194, v195
	global_store_dwordx2 v[32:33], v[200:201], off offset:512
	global_store_dwordx2 v[50:51], v[202:203], off offset:512
	v_pk_mul_f32 v[168:169], v[58:59], v[62:63] op_sel_hi:[1,0]
	v_pk_mul_f32 v[170:171], v[60:61], v[62:63] op_sel_hi:[1,0]
	v_pk_add_f32 v[172:173], v[160:161], 1.0 op_sel_hi:[1,0]
	v_pk_add_f32 v[174:175], v[162:163], 1.0 op_sel_hi:[1,0]
	v_pk_fma_f32 v[168:169], v[104:105], v[168:169], v[120:121]
	v_pk_fma_f32 v[170:171], v[106:107], v[170:171], v[122:123]
	s_nop 0
	v_pk_fma_f32 v[192:193], v[172:173], v[168:169], v[144:145]
	v_pk_fma_f32 v[194:195], v[174:175], v[170:171], v[146:147]
	v_cvt_pk_bf16_f32 v204, v168, v169
	v_cvt_pk_bf16_f32 v205, v170, v171
	v_cvt_pk_bf16_f32 v206, v192, v193
	v_cvt_pk_bf16_f32 v207, v194, v195
	global_store_dwordx2 v[32:33], v[204:205], off offset:1024
	global_store_dwordx2 v[50:51], v[206:207], off offset:1024
	v_pk_mul_f32 v[168:169], v[30:31], v[62:63] op_sel_hi:[1,0]
	v_pk_mul_f32 v[170:171], v[28:29], v[62:63] op_sel_hi:[1,0]
	v_pk_add_f32 v[172:173], v[164:165], 1.0 op_sel_hi:[1,0]
	v_pk_add_f32 v[174:175], v[166:167], 1.0 op_sel_hi:[1,0]
	v_pk_fma_f32 v[168:169], v[108:109], v[168:169], v[124:125]
	v_pk_fma_f32 v[170:171], v[110:111], v[170:171], v[126:127]
	s_nop 0
	v_pk_fma_f32 v[192:193], v[172:173], v[168:169], v[148:149]
	v_pk_fma_f32 v[194:195], v[174:175], v[170:171], v[150:151]
	v_cvt_pk_bf16_f32 v208, v168, v169
	v_cvt_pk_bf16_f32 v209, v170, v171
	v_cvt_pk_bf16_f32 v210, v192, v193
	v_cvt_pk_bf16_f32 v211, v194, v195
	global_store_dwordx2 v[32:33], v[208:209], off offset:1536
	global_store_dwordx2 v[50:51], v[210:211], off offset:1536
	v_cmp_lt_i32_e32 vcc, s22, v40
	v_add_u32_e32 v216, 0xffffe000, v40
	v_lshrrev_b32_e32 v216, 12, v216
	v_add_u32_e32 v216, 1, v216
	s_nop 0
	v_cndmask_b32_e32 v216, 0, v216, vcc
	v_mov_b64_e32 v[212:213], s[48:49]
	v_mad_u64_u32 v[212:213], s[38:39], v216, s23, v[212:213]
	s_mov_b64 s[38:39], 0x1000
	v_lshl_add_u64 v[212:213], v[212:213], 0, v[128:129]
	v_lshl_add_u64 v[214:215], v[212:213], 0, s[38:39]
	global_load_dwordx4 v[96:99], v[2:3], off
	global_load_dwordx4 v[112:115], v[4:5], off
	global_load_dwordx4 v[136:139], v[212:213], off
	global_load_dwordx4 v[152:155], v[214:215], off
	global_load_dwordx4 v[100:103], v[2:3], off offset:1024
	global_load_dwordx4 v[116:119], v[4:5], off offset:1024
	global_load_dwordx4 v[140:143], v[212:213], off offset:1024
	global_load_dwordx4 v[156:159], v[214:215], off offset:1024
	global_load_dwordx4 v[104:107], v[2:3], off offset:2048
	global_load_dwordx4 v[120:123], v[4:5], off offset:2048
	global_load_dwordx4 v[144:147], v[212:213], off offset:2048
	global_load_dwordx4 v[160:163], v[214:215], off offset:2048
	global_load_dwordx4 v[108:111], v[2:3], off offset:3072
	global_load_dwordx4 v[124:127], v[4:5], off offset:3072
	global_load_dwordx4 v[148:151], v[212:213], off offset:3072
	global_load_dwordx4 v[164:167], v[214:215], off offset:3072
	s_waitcnt vmcnt(24)
	v_mov_b32_e32 v24, v40
	v_mov_b32_e32 v32, v18
	v_mov_b32_e32 v33, v19
	v_mov_b32_e32 v30, v20
	v_mov_b32_e32 v31, v21
	v_mov_b32_e32 v28, v22
	v_mov_b32_e32 v29, v23
	v_mov_b32_e32 v26, v16
	v_mov_b32_e32 v27, v17
	s_andn2_b64 exec, exec, s[50:51]
	s_cbranch_execz .LBB0_933

.LBB0_1132:
	s_or_b64 exec, exec, s[44:45]
	v_lshlrev_b32_e32 v44, 16, v36
	v_and_b32_e32 v45, 0xffff0000, v36
	v_add_f32_e32 v1, 0, v44
	v_lshlrev_b32_e32 v46, 16, v37
	v_add_f32_e32 v1, v1, v45
	v_and_b32_e32 v47, 0xffff0000, v37
	v_add_f32_e32 v1, v1, v46
	v_lshlrev_b32_e32 v36, 16, v34
	v_add_f32_e32 v1, v1, v47
	v_and_b32_e32 v37, 0xffff0000, v34
	v_add_f32_e32 v1, v1, v36
	v_lshlrev_b32_e32 v34, 16, v35
	v_add_f32_e32 v1, v1, v37
	v_and_b32_e32 v35, 0xffff0000, v35
	v_add_f32_e32 v1, v1, v34
	v_lshlrev_b32_e32 v38, 16, v32
	v_add_f32_e32 v1, v1, v35
	v_and_b32_e32 v39, 0xffff0000, v32
	v_add_f32_e32 v1, v1, v38
	v_lshlrev_b32_e32 v32, 16, v33
	v_add_f32_e32 v1, v1, v39
	v_and_b32_e32 v33, 0xffff0000, v33
	v_add_f32_e32 v1, v1, v32
	v_lshlrev_b32_e32 v58, 16, v2
	v_add_f32_e32 v1, v1, v33
	v_and_b32_e32 v59, 0xffff0000, v2
	v_add_f32_e32 v1, v1, v58
	v_lshlrev_b32_e32 v2, 16, v3
	v_add_f32_e32 v1, v1, v59
	v_and_b32_e32 v3, 0xffff0000, v3
	v_add_f32_e32 v1, v1, v2
	v_add_f32_e32 v1, v1, v3
	v_cmp_lt_i32_e32 vcc, s22, v0
	s_mov_b64 s[44:45], -1
	v_lshlrev_b32_e32 v128, 2, v4
	s_waitcnt lgkmcnt(0)
	s_nop 1
	v_add_f32_dpp v1, v1, v1 quad_perm:[1,0,3,2] row_mask:0xf bank_mask:0xf
	s_nop 1
	v_add_f32_dpp v1, v1, v1 quad_perm:[2,3,0,1] row_mask:0xf bank_mask:0xf
	s_nop 1
	v_add_f32_dpp v1, v1, v1 row_half_mirror row_mask:0xf bank_mask:0xf
	s_nop 1
	v_add_f32_dpp v1, v1, v1 row_mirror row_mask:0xf bank_mask:0xf
	s_nop 1
	v_mov_b32_e32 v19, v1
	v_mov_b32_e32 v250, v1
	s_nop 1
	v_permlane16_swap_b32 v19, v250
	s_nop 1
	v_add_f32_e32 v1, v19, v250
	v_mov_b32_e32 v19, v1
	v_mov_b32_e32 v250, v1
	s_nop 1
	v_permlane32_swap_b32 v19, v250
	s_nop 1
	v_add_f32_e32 v1, v19, v250
	v_mul_f32_e32 v62, 0x3a800000, v1
	v_add_u32_e32 v1, 0xffffe000, v0
	v_lshrrev_b32_e32 v1, 12, v1
	v_add_u32_e32 v1, 1, v1
	v_pk_add_f32 v[40:41], v[38:39], v[62:63] op_sel_hi:[1,0] neg_lo:[0,1] neg_hi:[0,1]
	v_pk_add_f32 v[38:39], v[2:3], v[62:63] op_sel_hi:[1,0] neg_lo:[0,1] neg_hi:[0,1]
	v_cndmask_b32_e32 v2, 0, v1, vcc
	v_mov_b64_e32 v[0:1], s[50:51]
	v_pk_add_f32 v[48:49], v[36:37], v[62:63] op_sel_hi:[1,0] neg_lo:[0,1] neg_hi:[0,1]
	v_pk_add_f32 v[50:51], v[34:35], v[62:63] op_sel_hi:[1,0] neg_lo:[0,1] neg_hi:[0,1]
	v_pk_add_f32 v[36:37], v[58:59], v[62:63] op_sel_hi:[1,0] neg_lo:[0,1] neg_hi:[0,1]
	v_mad_u64_u32 v[34:35], s[2:3], v2, s23, v[0:1]
	global_load_dwordx4 v[0:3], v[6:7], off
	global_load_dwordx4 v[58:61], v[8:9], off
	v_pk_add_f32 v[44:45], v[44:45], v[62:63] op_sel_hi:[1,0] neg_lo:[0,1] neg_hi:[0,1]
	v_pk_add_f32 v[42:43], v[32:33], v[62:63] op_sel_hi:[1,0] neg_lo:[0,1] neg_hi:[0,1]
	v_pk_add_f32 v[76:77], v[46:47], v[62:63] op_sel_hi:[1,0] neg_lo:[0,1] neg_hi:[0,1]
	v_pk_mul_f32 v[62:63], v[44:45], v[44:45]
	v_pk_mul_f32 v[46:47], v[76:77], v[76:77]
	v_add_f32_e32 v19, v62, v63
	v_add_f32_e32 v19, v46, v19
	v_pk_mul_f32 v[64:65], v[48:49], v[48:49]
	v_add_f32_e32 v19, v47, v19
	v_add_f32_e32 v19, v64, v19
	v_pk_mul_f32 v[66:67], v[50:51], v[50:51]
	v_add_f32_e32 v19, v65, v19
	v_add_f32_e32 v19, v66, v19
	v_pk_mul_f32 v[68:69], v[40:41], v[40:41]
	v_add_f32_e32 v19, v67, v19
	v_add_f32_e32 v19, v68, v19
	v_pk_mul_f32 v[70:71], v[42:43], v[42:43]
	v_add_f32_e32 v19, v69, v19
	v_add_f32_e32 v19, v70, v19
	v_pk_mul_f32 v[72:73], v[36:37], v[36:37]
	v_add_f32_e32 v19, v71, v19
	v_add_f32_e32 v19, v72, v19
	v_pk_mul_f32 v[74:75], v[38:39], v[38:39]
	v_add_f32_e32 v19, v73, v19
	v_add_f32_e32 v19, v74, v19
	v_add_f32_e32 v19, v75, v19
	s_mov_b64 s[2:3], 0x1000
	v_lshl_add_u64 v[32:33], v[34:35], 0, s[2:3]
	s_waitcnt lgkmcnt(0)
	s_nop 1
	v_add_f32_dpp v19, v19, v19 quad_perm:[1,0,3,2] row_mask:0xf bank_mask:0xf
	s_nop 1
	v_add_f32_dpp v19, v19, v19 quad_perm:[2,3,0,1] row_mask:0xf bank_mask:0xf
	s_nop 1
	v_add_f32_dpp v19, v19, v19 row_half_mirror row_mask:0xf bank_mask:0xf
	s_nop 1
	v_add_f32_dpp v19, v19, v19 row_mirror row_mask:0xf bank_mask:0xf
	s_nop 1
	v_mov_b32_e32 v21, v19
	v_mov_b32_e32 v250, v19
	s_nop 1
	v_permlane16_swap_b32 v21, v250
	s_nop 1
	v_add_f32_e32 v19, v21, v250
	v_mov_b32_e32 v21, v19
	v_mov_b32_e32 v250, v19
	s_nop 1
	v_permlane32_swap_b32 v21, v250
	s_nop 1
	v_add_f32_e32 v19, v21, v250
	v_fmamk_f32 v19, v19, 0x3a800000, v182
	v_cmp_gt_f32_e32 vcc, s13, v19
	v_mul_f32_e32 v21, 0x4b800000, v19
	s_nop 0
	v_cndmask_b32_e32 v19, v19, v21, vcc
	v_rsq_f32_e32 v19, v19
	s_nop 0
	v_mul_f32_e32 v21, 0x45800000, v19
	v_cndmask_b32_e32 v46, v19, v21, vcc
	v_pk_mul_f32 v[44:45], v[44:45], v[46:47] op_sel_hi:[1,0]
	s_and_b64 vcc, exec, s[48:49]
	s_waitcnt vmcnt(0)
	v_pk_fma_f32 v[0:1], v[0:1], v[44:45], v[58:59]
	v_pk_mul_f32 v[44:45], v[76:77], v[46:47] op_sel_hi:[1,0]
	s_nop 0
	v_pk_fma_f32 v[2:3], v[2:3], v[44:45], v[60:61]
	v_lshl_add_u64 v[44:45], v[14:15], 0, v[10:11]
	s_cbranch_vccz .LBB0_1134
	v_lshl_add_u64 v[58:59], v[34:35], 0, v[128:129]
	v_lshl_add_u64 v[62:63], v[32:33], 0, v[128:129]
	global_load_dwordx4 v[58:61], v[58:59], off
	s_mov_b64 s[44:45], 0
	global_load_dwordx4 v[62:65], v[62:63], off
	s_waitcnt vmcnt(0)
	v_pk_add_f32 v[62:63], v[62:63], 1.0 op_sel_hi:[1,0]
	s_nop 0
	v_pk_fma_f32 v[58:59], v[0:1], v[62:63], v[58:59]
	v_pk_add_f32 v[62:63], v[64:65], 1.0 op_sel_hi:[1,0]
	v_add_co_u32_e32 v64, vcc, s25, v44
	v_pk_fma_f32 v[60:61], v[2:3], v[62:63], v[60:61]
	s_nop 0
	v_addc_co_u32_e32 v65, vcc, 0, v45, vcc
	v_cvt_pk_bf16_f32 v58, v58, v59
	v_cvt_pk_bf16_f32 v59, v60, v61
	v_add_co_u32_e32 v60, vcc, 0x1d600000, v44
	v_cvt_pk_bf16_f32 v62, v0, v1
	v_cvt_pk_bf16_f32 v63, v2, v3
	v_addc_co_u32_e32 v61, vcc, 0, v45, vcc
	global_store_dwordx2 v[64:65], v[62:63], off
	global_store_dwordx2 v[60:61], v[58:59], off
